# local barrier after P6 also without cache invalidate (P7 reads MERGED, which this CU cannot have in L1: P6 never loads it)
# speedup vs baseline: 1.0195x; 1.0021x over previous
.LBB0_1316:
	s_lshl_b32 s6, s6, 6
	s_add_i32 s82, s6, 0x500
	s_lshl_b64 s[8:9], s[82:83], 2
	s_add_u32 s8, s54, s8
	s_addc_u32 s9, s55, s9
	v_mov_b64_e32 v[4:5], s[8:9]
	flat_atomic_add v3, v[4:5], v228 sc0
	v_cvt_f32_u32_e32 v1, v2
	v_sub_u32_e32 v4, 0, v2
	v_rcp_iflag_f32_e32 v1, v1
	s_nop 0
	v_mul_f32_e32 v1, 0x4f7ffffe, v1
	v_cvt_u32_f32_e32 v1, v1
	v_mul_lo_u32 v4, v4, v1
	v_mul_hi_u32 v4, v1, v4
	v_add_u32_e32 v1, v1, v4
	s_waitcnt vmcnt(0) lgkmcnt(0)
	v_mul_hi_u32 v1, v3, v1
	v_mul_lo_u32 v4, v1, v2
	v_sub_u32_e32 v4, v3, v4
	v_cmp_ge_u32_e32 vcc, v4, v2
	v_add_u32_e32 v5, 1, v1
	s_nop 0
	v_cndmask_b32_e32 v1, v1, v5, vcc
	v_sub_u32_e32 v5, v4, v2
	v_cndmask_b32_e32 v4, v4, v5, vcc
	v_cmp_ge_u32_e32 vcc, v4, v2
	v_add_u32_e32 v4, 1, v1
	s_nop 0
	v_cndmask_b32_e32 v1, v1, v4, vcc
	v_add_u32_e32 v4, 1, v3
	v_mad_u64_u32 v[2:3], s[8:9], v2, v1, v[2:3]
	v_cmp_ne_u32_e32 vcc, v4, v2
	s_and_saveexec_b64 s[8:9], vcc
	s_xor_b64 s[12:13], exec, s[8:9]
	s_cbranch_execz .LBB0_1329
	s_cmp_eq_u32 s100, 0
	s_cbranch_scc1 .Lnf_6
	s_add_i32 s82, s6, 0x900
	s_lshl_b64 s[8:9], s[82:83], 2
	s_add_u32 s8, s54, s8
	s_addc_u32 s9, s55, s9
	v_mov_b64_e32 v[2:3], s[8:9]
.Lxg_6:
	flat_load_dword v234, v[2:3] sc1
	s_waitcnt vmcnt(0) lgkmcnt(0)
	v_cmp_ne_u32_e32 vcc, v234, v1
	s_cbranch_vccz .Lxg_6
	s_waitcnt vmcnt(0)
	s_branch .LBB0_1345
.Lnf_6:
	s_add_i32 s82, s6, 0x900
	s_lshl_b64 s[8:9], s[82:83], 2
	s_add_u32 s16, s54, 0x3400
	s_addc_u32 s17, s55, 0
	v_mov_b32_e32 v4, s101
	v_mad_u32_u24 v4, v4, v0, v0
	s_add_i32 s101, s101, 1
	v_mov_b64_e32 v[2:3], s[16:17]
	flat_load_dword v0, v[2:3] sc1
	s_waitcnt vmcnt(0) lgkmcnt(0)
	v_cmp_lt_u32_e32 vcc, v0, v4
	s_and_saveexec_b64 s[14:15], vcc
	s_cbranch_execz .LBB0_1328
	s_mov_b32 s7, 1
	s_mov_b64 s[18:19], 0
	s_branch .LBB0_1320

.LBB0_1329:
	s_andn2_saveexec_b64 s[8:9], s[12:13]
	s_cbranch_execz .LBB0_1345
	s_cmp_eq_u32 s100, 0
	s_cbranch_scc1 .Lfl_6
	s_add_i32 s82, s6, 0x900
	s_lshl_b64 s[8:9], s[82:83], 2
	s_add_u32 s8, s54, s8
	s_addc_u32 s9, s55, s9
	v_mov_b64_e32 v[0:1], s[8:9]
	flat_atomic_add v[0:1], v228
	s_waitcnt vmcnt(0)
	s_branch .LBB0_1345
